# P6 epilogue: counted wait before the second batch (does not drain the first batch's stores), second half's late x loads issued before the LDS round trip
# speedup vs baseline: 1.0179x; 1.0016x over previous
; template <class Epi>
; DI void gemm_tile256(const u16* __restrict__ Ag, long lda, const u16* __restrict__ Bg, long ldb, int nk, char* shm, Epi&& epi) {
;     ...
;   __syncthreads();
; #pragma unroll
;   for (int m = 0; m < 8; ++m)
; #pragma unroll
;     for (int n = 0; n < 4; ++n) epi(wr * 128 + m * 16 + fr, wc * 64 + n * 16 + fq * 4, acc[m][n]);
; DI void phase6(const Params& P, char* smem) {
;     ...
;     gemm_tile256(cat + (long)brow * 1024, 1024, WoT + (long)bcol * 1024, 1024, 32, smem, [&](int row, int col0, f32x4 v) {
;       const long o = (long)(brow + row) * 1024 + bcol + col0;
;       const float4 xs = *reinterpret_cast<const float4*>(P.x + o);
;       *reinterpret_cast<float4*>(Z1 + o) = make_float4(ALPHA * xs.x + v[0], ALPHA * xs.y + v[1], ALPHA * xs.z + v[2], ALPHA * xs.w + v[3]);
;     });
.Lgemm_p6_kend:
	s_nop 7
	s_nop 3
	s_waitcnt vmcnt(0) lgkmcnt(0)
	s_barrier
	v_and_b32_e32 v196, 15, v208
	v_lshrrev_b32_e32 v197, 4, v208
	v_lshrrev_b32_e32 v198, 6, v189
	v_lshlrev_b32_e32 v198, 14, v198
	v_lshl_add_u32 v201, v196, 8, v198
	v_or_b32_e32 v199, 0, v197
	v_xor_b32_e32 v199, v199, v196
	v_lshl_add_u32 v206, v199, 4, v201
	v_or_b32_e32 v199, 4, v197
	v_xor_b32_e32 v199, v199, v196
	v_lshl_add_u32 v207, v199, 4, v201
	v_or_b32_e32 v199, 8, v197
	v_xor_b32_e32 v199, v199, v196
	v_lshl_add_u32 v210, v199, 4, v201
	v_or_b32_e32 v199, 12, v197
	v_xor_b32_e32 v199, v199, v196
	v_lshl_add_u32 v211, v199, 4, v201
	v_add_u32_e32 v200, 0, v197
	v_xor_b32_e32 v199, v196, v200
	v_lshl_add_u32 v212, v200, 8, v198
	v_lshl_add_u32 v212, v199, 4, v212
	v_add_u32_e32 v200, 4, v197
	v_xor_b32_e32 v199, v196, v200
	v_lshl_add_u32 v213, v200, 8, v198
	v_lshl_add_u32 v213, v199, 4, v213
	v_add_u32_e32 v200, 8, v197
	v_xor_b32_e32 v199, v196, v200
	v_lshl_add_u32 v214, v200, 8, v198
	v_lshl_add_u32 v214, v199, 4, v214
	v_add_u32_e32 v200, 12, v197
	v_xor_b32_e32 v199, v196, v200
	v_lshl_add_u32 v215, v200, 8, v198
	v_lshl_add_u32 v215, v199, 4, v215
	v_lshl_add_u32 v199, v190, 7, v197
	v_add_u32_e32 v199, s10, v199
	v_lshlrev_b32_e32 v216, 12, v199
	v_bfe_u32 v199, v189, 6, 2
	v_lshl_add_u32 v216, v199, 8, v216
	v_lshl_add_u32 v216, v196, 4, v216
	s_and_b32 s26, s74, 3
	s_lshl_b32 s26, s26, 10
	v_add_u32_e32 v216, s26, v216
	v_add_u32_e32 v201, 0x0, v216
	global_load_dwordx4 v[218:221], v201, s[52:53]
	v_add_u32_e32 v202, 0x4000, v216
	global_load_dwordx4 v[222:225], v202, s[52:53]
	v_add_u32_e32 v201, 0x8000, v216
	global_load_dwordx4 v[226:229], v201, s[52:53]
	v_add_u32_e32 v202, 0xc000, v216
	global_load_dwordx4 v[230:233], v202, s[52:53]
	v_add_u32_e32 v201, 0x10000, v216
	global_load_dwordx4 v[234:237], v201, s[52:53]
	v_add_u32_e32 v202, 0x14000, v216
	global_load_dwordx4 v[238:241], v202, s[52:53]
	v_add_u32_e32 v201, 0x18000, v216
	global_load_dwordx4 v[242:245], v201, s[52:53]
	v_add_u32_e32 v202, 0x1c000, v216
	global_load_dwordx4 v[246:249], v202, s[52:53]
	ds_write_b128 v206, v[124:127] offset:0
	ds_write_b128 v207, v[120:123] offset:0
	ds_write_b128 v210, v[116:119] offset:0
	ds_write_b128 v211, v[112:115] offset:0
	ds_write_b128 v206, v[108:111] offset:4096
	ds_write_b128 v207, v[104:107] offset:4096
	ds_write_b128 v210, v[100:103] offset:4096
	ds_write_b128 v211, v[96:99] offset:4096
	ds_write_b128 v206, v[92:95] offset:8192
	ds_write_b128 v207, v[88:91] offset:8192
	ds_write_b128 v210, v[84:87] offset:8192
	ds_write_b128 v211, v[80:83] offset:8192
	ds_write_b128 v206, v[76:79] offset:12288
	ds_write_b128 v207, v[72:75] offset:12288
	ds_write_b128 v210, v[68:71] offset:12288
	ds_write_b128 v211, v[64:67] offset:12288
	s_waitcnt lgkmcnt(0)
	v_add_u32_e32 v201, 0x20000, v216
	global_load_dwordx4 v[64:67], v201, s[52:53]
	v_add_u32_e32 v202, 0x24000, v216
	global_load_dwordx4 v[68:71], v202, s[52:53]
	v_add_u32_e32 v201, 0x28000, v216
	global_load_dwordx4 v[72:75], v201, s[52:53]
	v_add_u32_e32 v202, 0x2c000, v216
	global_load_dwordx4 v[76:79], v202, s[52:53]
	v_add_u32_e32 v201, 0x30000, v216
	global_load_dwordx4 v[80:83], v201, s[52:53]
	v_add_u32_e32 v202, 0x34000, v216
	global_load_dwordx4 v[84:87], v202, s[52:53]
	v_add_u32_e32 v201, 0x38000, v216
	global_load_dwordx4 v[88:91], v201, s[52:53]
	v_add_u32_e32 v202, 0x3c000, v216
	global_load_dwordx4 v[92:95], v202, s[52:53]
	ds_read_b128 v[96:99], v212 offset:0
	ds_read_b128 v[100:103], v213 offset:0
	ds_read_b128 v[104:107], v214 offset:0
	ds_read_b128 v[108:111], v215 offset:0
	ds_read_b128 v[112:115], v212 offset:4096
	ds_read_b128 v[116:119], v213 offset:4096
	ds_read_b128 v[120:123], v214 offset:4096
	ds_read_b128 v[124:127], v215 offset:4096
	s_waitcnt vmcnt(8)
	s_waitcnt lgkmcnt(7)
	v_pk_fma_f32 v[218:219], v[218:219], s[6:7], v[96:97] op_sel_hi:[1,0,1]
	v_pk_fma_f32 v[220:221], v[220:221], s[6:7], v[98:99] op_sel_hi:[1,0,1]
	v_add_u32_e32 v201, 0x0, v216
	global_store_dwordx4 v201, v[218:221], s[38:39]
	s_waitcnt lgkmcnt(6)
	v_pk_fma_f32 v[222:223], v[222:223], s[6:7], v[100:101] op_sel_hi:[1,0,1]
	v_pk_fma_f32 v[224:225], v[224:225], s[6:7], v[102:103] op_sel_hi:[1,0,1]
	v_add_u32_e32 v202, 0x4000, v216
	global_store_dwordx4 v202, v[222:225], s[38:39]
	s_waitcnt lgkmcnt(5)
	v_pk_fma_f32 v[226:227], v[226:227], s[6:7], v[104:105] op_sel_hi:[1,0,1]
	v_pk_fma_f32 v[228:229], v[228:229], s[6:7], v[106:107] op_sel_hi:[1,0,1]
	v_add_u32_e32 v201, 0x8000, v216
	global_store_dwordx4 v201, v[226:229], s[38:39]
	s_waitcnt lgkmcnt(4)
	v_pk_fma_f32 v[230:231], v[230:231], s[6:7], v[108:109] op_sel_hi:[1,0,1]
	v_pk_fma_f32 v[232:233], v[232:233], s[6:7], v[110:111] op_sel_hi:[1,0,1]
	v_add_u32_e32 v202, 0xc000, v216
	global_store_dwordx4 v202, v[230:233], s[38:39]
	s_waitcnt lgkmcnt(3)
	v_pk_fma_f32 v[234:235], v[234:235], s[6:7], v[112:113] op_sel_hi:[1,0,1]
	v_pk_fma_f32 v[236:237], v[236:237], s[6:7], v[114:115] op_sel_hi:[1,0,1]
	v_add_u32_e32 v201, 0x10000, v216
	global_store_dwordx4 v201, v[234:237], s[38:39]
	s_waitcnt lgkmcnt(2)
	v_pk_fma_f32 v[238:239], v[238:239], s[6:7], v[116:117] op_sel_hi:[1,0,1]
	v_pk_fma_f32 v[240:241], v[240:241], s[6:7], v[118:119] op_sel_hi:[1,0,1]
	v_add_u32_e32 v202, 0x14000, v216
	global_store_dwordx4 v202, v[238:241], s[38:39]
	s_waitcnt lgkmcnt(1)
	v_pk_fma_f32 v[242:243], v[242:243], s[6:7], v[120:121] op_sel_hi:[1,0,1]
	v_pk_fma_f32 v[244:245], v[244:245], s[6:7], v[122:123] op_sel_hi:[1,0,1]
	v_add_u32_e32 v201, 0x18000, v216
	global_store_dwordx4 v201, v[242:245], s[38:39]
	s_waitcnt lgkmcnt(0)
; DI void phase6(const Params& P, char* smem) {
;     ...
;     gemm_tile256(cat + (long)brow * 1024, 1024, WoT + (long)bcol * 1024, 1024, 32, smem, [&](int row, int col0, f32x4 v) {
;       const long o = (long)(brow + row) * 1024 + bcol + col0;
;       const float4 xs = *reinterpret_cast<const float4*>(P.x + o);
;       *reinterpret_cast<float4*>(Z1 + o) = make_float4(ALPHA * xs.x + v[0], ALPHA * xs.y + v[1], ALPHA * xs.z + v[2], ALPHA * xs.w + v[3]);
;     });
	v_pk_fma_f32 v[246:247], v[246:247], s[6:7], v[124:125] op_sel_hi:[1,0,1]
	v_pk_fma_f32 v[248:249], v[248:249], s[6:7], v[126:127] op_sel_hi:[1,0,1]
	v_add_u32_e32 v202, 0x1c000, v216
	global_store_dwordx4 v202, v[246:249], s[38:39]
	ds_read_b128 v[96:99], v212 offset:8192
	ds_read_b128 v[100:103], v213 offset:8192
	ds_read_b128 v[104:107], v214 offset:8192
	ds_read_b128 v[108:111], v215 offset:8192
	ds_read_b128 v[112:115], v212 offset:12288
	ds_read_b128 v[116:119], v213 offset:12288
	ds_read_b128 v[120:123], v214 offset:12288
	ds_read_b128 v[124:127], v215 offset:12288
	s_waitcnt vmcnt(8)
	s_waitcnt lgkmcnt(7)
	v_pk_fma_f32 v[64:65], v[64:65], s[6:7], v[96:97] op_sel_hi:[1,0,1]
	v_pk_fma_f32 v[66:67], v[66:67], s[6:7], v[98:99] op_sel_hi:[1,0,1]
	v_add_u32_e32 v201, 0x20000, v216
	global_store_dwordx4 v201, v[64:67], s[38:39]
	s_waitcnt lgkmcnt(6)
	v_pk_fma_f32 v[68:69], v[68:69], s[6:7], v[100:101] op_sel_hi:[1,0,1]
	v_pk_fma_f32 v[70:71], v[70:71], s[6:7], v[102:103] op_sel_hi:[1,0,1]
	v_add_u32_e32 v202, 0x24000, v216
	global_store_dwordx4 v202, v[68:71], s[38:39]
	s_waitcnt lgkmcnt(5)
	v_pk_fma_f32 v[72:73], v[72:73], s[6:7], v[104:105] op_sel_hi:[1,0,1]
	v_pk_fma_f32 v[74:75], v[74:75], s[6:7], v[106:107] op_sel_hi:[1,0,1]
	v_add_u32_e32 v201, 0x28000, v216
	global_store_dwordx4 v201, v[72:75], s[38:39]
	s_waitcnt lgkmcnt(4)
	v_pk_fma_f32 v[76:77], v[76:77], s[6:7], v[108:109] op_sel_hi:[1,0,1]
	v_pk_fma_f32 v[78:79], v[78:79], s[6:7], v[110:111] op_sel_hi:[1,0,1]
	v_add_u32_e32 v202, 0x2c000, v216
	global_store_dwordx4 v202, v[76:79], s[38:39]
	s_waitcnt lgkmcnt(3)
	v_pk_fma_f32 v[80:81], v[80:81], s[6:7], v[112:113] op_sel_hi:[1,0,1]
	v_pk_fma_f32 v[82:83], v[82:83], s[6:7], v[114:115] op_sel_hi:[1,0,1]
	v_add_u32_e32 v201, 0x30000, v216
	global_store_dwordx4 v201, v[80:83], s[38:39]
	s_waitcnt lgkmcnt(2)
	v_pk_fma_f32 v[84:85], v[84:85], s[6:7], v[116:117] op_sel_hi:[1,0,1]
	v_pk_fma_f32 v[86:87], v[86:87], s[6:7], v[118:119] op_sel_hi:[1,0,1]
	v_add_u32_e32 v202, 0x34000, v216
	global_store_dwordx4 v202, v[84:87], s[38:39]
	s_waitcnt lgkmcnt(1)
	v_pk_fma_f32 v[88:89], v[88:89], s[6:7], v[120:121] op_sel_hi:[1,0,1]
	v_pk_fma_f32 v[90:91], v[90:91], s[6:7], v[122:123] op_sel_hi:[1,0,1]
	v_add_u32_e32 v201, 0x38000, v216
	global_store_dwordx4 v201, v[88:91], s[38:39]
	s_waitcnt lgkmcnt(0)
	v_pk_fma_f32 v[92:93], v[92:93], s[6:7], v[124:125] op_sel_hi:[1,0,1]
	v_pk_fma_f32 v[94:95], v[94:95], s[6:7], v[126:127] op_sel_hi:[1,0,1]
	v_add_u32_e32 v202, 0x3c000, v216
	global_store_dwordx4 v202, v[92:95], s[38:39]
	s_waitcnt lgkmcnt(0)
	v_add_u32_e32 v201, 0x40000, v216
	global_load_dwordx4 v[218:221], v201, s[52:53]
	v_add_u32_e32 v202, 0x44000, v216
	global_load_dwordx4 v[222:225], v202, s[52:53]
	v_add_u32_e32 v201, 0x48000, v216
	global_load_dwordx4 v[226:229], v201, s[52:53]
	v_add_u32_e32 v202, 0x4c000, v216
	global_load_dwordx4 v[230:233], v202, s[52:53]
	v_add_u32_e32 v201, 0x50000, v216
	global_load_dwordx4 v[234:237], v201, s[52:53]
	v_add_u32_e32 v202, 0x54000, v216
	global_load_dwordx4 v[238:241], v202, s[52:53]
	v_add_u32_e32 v201, 0x58000, v216
	global_load_dwordx4 v[242:245], v201, s[52:53]
	v_add_u32_e32 v202, 0x5c000, v216
	global_load_dwordx4 v[246:249], v202, s[52:53]
	ds_write_b128 v206, v[60:63] offset:0
	ds_write_b128 v207, v[56:59] offset:0
	ds_write_b128 v210, v[52:55] offset:0
	ds_write_b128 v211, v[48:51] offset:0
	ds_write_b128 v206, v[44:47] offset:4096
	ds_write_b128 v207, v[40:43] offset:4096
	ds_write_b128 v210, v[36:39] offset:4096
	ds_write_b128 v211, v[32:35] offset:4096
	ds_write_b128 v206, v[28:31] offset:8192
	ds_write_b128 v207, v[24:27] offset:8192
	ds_write_b128 v210, v[20:23] offset:8192
	ds_write_b128 v211, v[16:19] offset:8192
	ds_write_b128 v206, v[12:15] offset:12288
	ds_write_b128 v207, v[8:11] offset:12288
	ds_write_b128 v210, v[4:7] offset:12288
	ds_write_b128 v211, v[0:3] offset:12288
	v_add_u32_e32 v201, 0x60000, v216
	global_load_dwordx4 v[64:67], v201, s[52:53]
	v_add_u32_e32 v202, 0x64000, v216
	global_load_dwordx4 v[68:71], v202, s[52:53]
	v_add_u32_e32 v201, 0x68000, v216
	global_load_dwordx4 v[72:75], v201, s[52:53]
	v_add_u32_e32 v202, 0x6c000, v216
	global_load_dwordx4 v[76:79], v202, s[52:53]
	v_add_u32_e32 v201, 0x70000, v216
	global_load_dwordx4 v[80:83], v201, s[52:53]
	v_add_u32_e32 v202, 0x74000, v216
	global_load_dwordx4 v[84:87], v202, s[52:53]
	v_add_u32_e32 v201, 0x78000, v216
	global_load_dwordx4 v[88:91], v201, s[52:53]
	v_add_u32_e32 v202, 0x7c000, v216
	global_load_dwordx4 v[92:95], v202, s[52:53]
	s_waitcnt lgkmcnt(0)
; DI void phase6(const Params& P, char* smem) {
;     ...
;     gemm_tile256(cat + (long)brow * 1024, 1024, WoT + (long)bcol * 1024, 1024, 32, smem, [&](int row, int col0, f32x4 v) {
;       const long o = (long)(brow + row) * 1024 + bcol + col0;
;       const float4 xs = *reinterpret_cast<const float4*>(P.x + o);
;       *reinterpret_cast<float4*>(Z1 + o) = make_float4(ALPHA * xs.x + v[0], ALPHA * xs.y + v[1], ALPHA * xs.z + v[2], ALPHA * xs.w + v[3]);
;     });
	ds_read_b128 v[96:99], v212 offset:0
	ds_read_b128 v[100:103], v213 offset:0
	ds_read_b128 v[104:107], v214 offset:0
	ds_read_b128 v[108:111], v215 offset:0
	ds_read_b128 v[112:115], v212 offset:4096
	ds_read_b128 v[116:119], v213 offset:4096
	ds_read_b128 v[120:123], v214 offset:4096
	ds_read_b128 v[124:127], v215 offset:4096
	s_waitcnt vmcnt(8)
	s_waitcnt lgkmcnt(7)
	v_pk_fma_f32 v[218:219], v[218:219], s[6:7], v[96:97] op_sel_hi:[1,0,1]
	v_pk_fma_f32 v[220:221], v[220:221], s[6:7], v[98:99] op_sel_hi:[1,0,1]
	v_add_u32_e32 v201, 0x40000, v216
	global_store_dwordx4 v201, v[218:221], s[38:39]
	s_waitcnt lgkmcnt(6)
	v_pk_fma_f32 v[222:223], v[222:223], s[6:7], v[100:101] op_sel_hi:[1,0,1]
	v_pk_fma_f32 v[224:225], v[224:225], s[6:7], v[102:103] op_sel_hi:[1,0,1]
	v_add_u32_e32 v202, 0x44000, v216
	global_store_dwordx4 v202, v[222:225], s[38:39]
	s_waitcnt lgkmcnt(5)
	v_pk_fma_f32 v[226:227], v[226:227], s[6:7], v[104:105] op_sel_hi:[1,0,1]
	v_pk_fma_f32 v[228:229], v[228:229], s[6:7], v[106:107] op_sel_hi:[1,0,1]
	v_add_u32_e32 v201, 0x48000, v216
	global_store_dwordx4 v201, v[226:229], s[38:39]
	s_waitcnt lgkmcnt(4)
	v_pk_fma_f32 v[230:231], v[230:231], s[6:7], v[108:109] op_sel_hi:[1,0,1]
	v_pk_fma_f32 v[232:233], v[232:233], s[6:7], v[110:111] op_sel_hi:[1,0,1]
	v_add_u32_e32 v202, 0x4c000, v216
	global_store_dwordx4 v202, v[230:233], s[38:39]
	s_waitcnt lgkmcnt(3)
	v_pk_fma_f32 v[234:235], v[234:235], s[6:7], v[112:113] op_sel_hi:[1,0,1]
	v_pk_fma_f32 v[236:237], v[236:237], s[6:7], v[114:115] op_sel_hi:[1,0,1]
	v_add_u32_e32 v201, 0x50000, v216
	global_store_dwordx4 v201, v[234:237], s[38:39]
	s_waitcnt lgkmcnt(2)
	v_pk_fma_f32 v[238:239], v[238:239], s[6:7], v[116:117] op_sel_hi:[1,0,1]
	v_pk_fma_f32 v[240:241], v[240:241], s[6:7], v[118:119] op_sel_hi:[1,0,1]
	v_add_u32_e32 v202, 0x54000, v216
	global_store_dwordx4 v202, v[238:241], s[38:39]
	s_waitcnt lgkmcnt(1)
	v_pk_fma_f32 v[242:243], v[242:243], s[6:7], v[120:121] op_sel_hi:[1,0,1]
	v_pk_fma_f32 v[244:245], v[244:245], s[6:7], v[122:123] op_sel_hi:[1,0,1]
	v_add_u32_e32 v201, 0x58000, v216
	global_store_dwordx4 v201, v[242:245], s[38:39]
	s_waitcnt lgkmcnt(0)
	v_pk_fma_f32 v[246:247], v[246:247], s[6:7], v[124:125] op_sel_hi:[1,0,1]
	v_pk_fma_f32 v[248:249], v[248:249], s[6:7], v[126:127] op_sel_hi:[1,0,1]
	v_add_u32_e32 v202, 0x5c000, v216
	global_store_dwordx4 v202, v[246:249], s[38:39]
	ds_read_b128 v[96:99], v212 offset:8192
	ds_read_b128 v[100:103], v213 offset:8192
	ds_read_b128 v[104:107], v214 offset:8192
	ds_read_b128 v[108:111], v215 offset:8192
	ds_read_b128 v[112:115], v212 offset:12288
	ds_read_b128 v[116:119], v213 offset:12288
	ds_read_b128 v[120:123], v214 offset:12288
	ds_read_b128 v[124:127], v215 offset:12288
	s_waitcnt vmcnt(8)
	s_waitcnt lgkmcnt(7)
	v_pk_fma_f32 v[64:65], v[64:65], s[6:7], v[96:97] op_sel_hi:[1,0,1]
	v_pk_fma_f32 v[66:67], v[66:67], s[6:7], v[98:99] op_sel_hi:[1,0,1]
	v_add_u32_e32 v201, 0x60000, v216
	global_store_dwordx4 v201, v[64:67], s[38:39]
	s_waitcnt lgkmcnt(6)
	v_pk_fma_f32 v[68:69], v[68:69], s[6:7], v[100:101] op_sel_hi:[1,0,1]
	v_pk_fma_f32 v[70:71], v[70:71], s[6:7], v[102:103] op_sel_hi:[1,0,1]
	v_add_u32_e32 v202, 0x64000, v216
	global_store_dwordx4 v202, v[68:71], s[38:39]
	s_waitcnt lgkmcnt(5)
	v_pk_fma_f32 v[72:73], v[72:73], s[6:7], v[104:105] op_sel_hi:[1,0,1]
	v_pk_fma_f32 v[74:75], v[74:75], s[6:7], v[106:107] op_sel_hi:[1,0,1]
	v_add_u32_e32 v201, 0x68000, v216
	global_store_dwordx4 v201, v[72:75], s[38:39]
	s_waitcnt lgkmcnt(4)
	v_pk_fma_f32 v[76:77], v[76:77], s[6:7], v[108:109] op_sel_hi:[1,0,1]
	v_pk_fma_f32 v[78:79], v[78:79], s[6:7], v[110:111] op_sel_hi:[1,0,1]
	v_add_u32_e32 v202, 0x6c000, v216
	global_store_dwordx4 v202, v[76:79], s[38:39]
	s_waitcnt lgkmcnt(3)
	v_pk_fma_f32 v[80:81], v[80:81], s[6:7], v[112:113] op_sel_hi:[1,0,1]
	v_pk_fma_f32 v[82:83], v[82:83], s[6:7], v[114:115] op_sel_hi:[1,0,1]
	v_add_u32_e32 v201, 0x70000, v216
	global_store_dwordx4 v201, v[80:83], s[38:39]
	s_waitcnt lgkmcnt(2)
	v_pk_fma_f32 v[84:85], v[84:85], s[6:7], v[116:117] op_sel_hi:[1,0,1]
	v_pk_fma_f32 v[86:87], v[86:87], s[6:7], v[118:119] op_sel_hi:[1,0,1]
	v_add_u32_e32 v202, 0x74000, v216
	global_store_dwordx4 v202, v[84:87], s[38:39]
	s_waitcnt lgkmcnt(1)
	v_pk_fma_f32 v[88:89], v[88:89], s[6:7], v[120:121] op_sel_hi:[1,0,1]
	v_pk_fma_f32 v[90:91], v[90:91], s[6:7], v[122:123] op_sel_hi:[1,0,1]
	v_add_u32_e32 v201, 0x78000, v216
	global_store_dwordx4 v201, v[88:91], s[38:39]
	s_waitcnt lgkmcnt(0)
	v_pk_fma_f32 v[92:93], v[92:93], s[6:7], v[124:125] op_sel_hi:[1,0,1]
	v_pk_fma_f32 v[94:95], v[94:95], s[6:7], v[126:127] op_sel_hi:[1,0,1]
	v_add_u32_e32 v202, 0x7c000, v216
	global_store_dwordx4 v202, v[92:95], s[38:39]
	s_add_i32 s15, s15, s9
	s_add_i32 s4, s4, s14
	s_cmp_lt_i32 s15, 64
	s_cbranch_scc1 .LBB0_946
